# v122 + non-temporal hint on the last-use f32 residual loads of the P6 epilogue (same policy as the P0 row loads)
# baseline (speedup 1.0000x reference)
.LBB0_1022:
	v_mov_b32_e32 v142, v146
	v_mov_b32_e32 v143, v1
	v_mov_b32_e32 v153, v147
	v_mov_b32_e32 v144, v165
	s_lshl_b32 s1, s24, 8
	s_add_i32 s1, s1, s39
	v_add_u32_e32 v144, s1, v142
	s_lshl_b32 s0, s0, 8
	s_or_b32 s0, s0, s40
	v_ashrrev_i32_e32 v145, 31, v144
	v_lshl_add_u32 v142, v153, 3, s0
	v_lshlrev_b64 v[154:155], 13, v[144:145]
	v_lshl_add_u64 v[154:155], s[60:61], 0, v[154:155]
	v_ashrrev_i32_e32 v143, 31, v142
	v_lshl_add_u64 v[162:163], v[142:143], 2, v[154:155]
	global_load_dwordx4 v[154:157], v[162:163], off nt
	global_load_dwordx4 v[158:161], v[162:163], off offset:16 nt
	global_load_dwordx4 v[170:173], v[162:163], off offset:512 nt
	global_load_dwordx4 v[174:177], v[162:163], off offset:528 nt
	v_lshlrev_b64 v[166:167], 12, v[144:145]
	v_lshl_add_u64 v[166:167], s[62:63], 0, v[166:167]
	v_lshl_add_u64 v[166:167], v[142:143], 1, v[166:167]
	v_cmp_eq_u32_e32 vcc, 0, v153
	s_waitcnt vmcnt(2)
	v_pk_add_f32 v[128:129], v[128:129], v[156:157]
	v_pk_add_f32 v[168:169], v[126:127], v[154:155]
	v_pk_add_f32 v[160:161], v[124:125], v[160:161]
	v_pk_add_f32 v[158:159], v[122:123], v[158:159]
	v_cvt_pk_bf16_f32 v122, v168, v169
	v_cvt_pk_bf16_f32 v123, v128, v129
	v_mul_f32_e32 v153, v169, v169
	v_cvt_pk_bf16_f32 v124, v158, v159
	v_cvt_pk_bf16_f32 v125, v160, v161
	global_store_dwordx4 v[166:167], v[122:125], off
	s_nop 0
	s_nop 0
	s_nop 0
	v_mul_f32_e32 v129, v129, v129
	v_mul_f32_e32 v159, v159, v159
	v_fmac_f32_e32 v153, v168, v168
	v_fmac_f32_e32 v129, v128, v128
	v_mul_f32_e32 v161, v161, v161
	v_fmac_f32_e32 v159, v158, v158
	v_add_f32_e32 v128, v153, v129
	v_fmac_f32_e32 v161, v160, v160
	v_add_f32_e32 v128, v128, v159
	v_add_f32_e32 v153, v161, v128
	v_and_b32_e32 v123, 64, v152
	v_xor_b32_e32 v122, 16, v152
	v_add_u32_e32 v123, 64, v123
	v_cmp_lt_i32_e64 s[0:1], v122, v123
	v_xor_b32_e32 v162, 32, v152
	s_waitcnt vmcnt(2)
	v_pk_add_f32 v[120:121], v[120:121], v[172:173]
	v_pk_add_f32 v[118:119], v[118:119], v[170:171]
	s_waitcnt vmcnt(1)
	v_pk_add_f32 v[128:129], v[116:117], v[176:177]
	v_pk_add_f32 v[114:115], v[114:115], v[174:175]
	v_mul_f32_e32 v116, v119, v119
	v_mul_f32_e32 v117, v121, v121
	v_mul_f32_e32 v124, v115, v115
	v_fmac_f32_e32 v116, v118, v118
	v_fmac_f32_e32 v117, v120, v120
	v_mul_f32_e32 v125, v129, v129
	v_fmac_f32_e32 v124, v114, v114
	v_add_f32_e32 v116, v116, v117
	v_fmac_f32_e32 v125, v128, v128
	v_add_f32_e32 v116, v116, v124
	v_cndmask_b32_e64 v122, v152, v122, s[0:1]
	v_add_f32_e32 v116, v125, v116
	v_lshlrev_b32_e32 v122, 2, v122
	v_add_f32_e32 v116, v153, v116
	ds_bpermute_b32 v117, v122, v116
	v_cmp_lt_i32_e64 s[0:1], v162, v123
	v_cvt_pk_bf16_f32 v124, v118, v119
	v_cvt_pk_bf16_f32 v125, v120, v121
	v_cvt_pk_bf16_f32 v126, v114, v115
	s_waitcnt lgkmcnt(0)
	v_add_f32_e32 v117, v116, v117
	v_lshl_add_u64 v[114:115], v[144:145], 2, s[84:85]
	v_cndmask_b32_e64 v123, v152, v162, s[0:1]
	v_lshlrev_b32_e32 v116, 2, v123
	ds_bpermute_b32 v118, v116, v117
	v_cvt_pk_bf16_f32 v127, v128, v129
	global_store_dwordx4 v[166:167], v[124:127], off offset:256
	s_and_saveexec_b64 s[0:1], vcc
	s_cbranch_execz .LBB0_1024
	s_waitcnt lgkmcnt(0)
	v_add_f32_e32 v117, v117, v118
	global_atomic_add_f32 v[114:115], v117, off
.LBB0_1024:
	s_or_b64 exec, exec, s[0:1]
	v_add_u32_e32 v128, 16, v144
	v_ashrrev_i32_e32 v129, 31, v128
	s_waitcnt lgkmcnt(0)
	v_lshlrev_b64 v[118:119], 13, v[128:129]
	v_lshl_add_u64 v[118:119], s[60:61], 0, v[118:119]
	v_lshl_add_u64 v[154:155], v[142:143], 2, v[118:119]
	global_load_dwordx4 v[118:121], v[154:155], off nt
	global_load_dwordx4 v[124:127], v[154:155], off offset:16 nt
	global_load_dwordx4 v[170:173], v[154:155], off offset:512 nt
	global_load_dwordx4 v[174:177], v[154:155], off offset:528 nt
	v_lshlrev_b64 v[128:129], 12, v[128:129]
	v_lshl_add_u64 v[128:129], s[62:63], 0, v[128:129]
	v_lshl_add_u64 v[128:129], v[142:143], 1, v[128:129]
	s_waitcnt vmcnt(3)
	v_pk_add_f32 v[120:121], v[112:113], v[120:121]
	v_pk_add_f32 v[118:119], v[110:111], v[118:119]
	s_waitcnt vmcnt(2)
	v_pk_add_f32 v[126:127], v[108:109], v[126:127]
	v_pk_add_f32 v[124:125], v[106:107], v[124:125]
	v_cvt_pk_bf16_f32 v106, v118, v119
	v_cvt_pk_bf16_f32 v107, v120, v121
	v_mul_f32_e32 v117, v119, v119
	v_cvt_pk_bf16_f32 v108, v124, v125
	v_cvt_pk_bf16_f32 v109, v126, v127
	global_store_dwordx4 v[128:129], v[106:109], off
	s_nop 0
	s_nop 0
	s_nop 0
	v_mul_f32_e32 v119, v121, v121
	v_mul_f32_e32 v121, v125, v125
	v_fmac_f32_e32 v117, v118, v118
	v_fmac_f32_e32 v119, v120, v120
	v_mul_f32_e32 v123, v127, v127
	v_fmac_f32_e32 v121, v124, v124
	v_add_f32_e32 v117, v117, v119
	v_fmac_f32_e32 v123, v126, v126
	v_add_f32_e32 v117, v117, v121
	v_add_f32_e32 v117, v123, v117
	s_waitcnt vmcnt(2)
	v_pk_add_f32 v[104:105], v[104:105], v[172:173]
	v_pk_add_f32 v[102:103], v[102:103], v[170:171]
	s_waitcnt vmcnt(1)
	v_pk_add_f32 v[108:109], v[98:99], v[174:175]
	v_mul_f32_e32 v98, v103, v103
	v_mul_f32_e32 v99, v105, v105
	v_pk_add_f32 v[106:107], v[100:101], v[176:177]
	v_mul_f32_e32 v100, v109, v109
	v_fmac_f32_e32 v98, v102, v102
	v_fmac_f32_e32 v99, v104, v104
	v_mul_f32_e32 v101, v107, v107
	v_fmac_f32_e32 v100, v108, v108
	v_add_f32_e32 v98, v98, v99
	v_add_f32_e32 v98, v98, v100
	v_fmac_f32_e32 v101, v106, v106
	v_add_f32_e32 v98, v101, v98
	v_add_f32_e32 v98, v117, v98
	ds_bpermute_b32 v99, v122, v98
	v_cvt_pk_bf16_f32 v100, v102, v103
	v_cvt_pk_bf16_f32 v101, v104, v105
	v_cvt_pk_bf16_f32 v102, v108, v109
	v_cvt_pk_bf16_f32 v103, v106, v107
	s_waitcnt lgkmcnt(0)
	v_add_f32_e32 v98, v98, v99
	ds_bpermute_b32 v99, v116, v98
	global_store_dwordx4 v[128:129], v[100:103], off offset:256
	s_and_saveexec_b64 s[0:1], vcc
	s_cbranch_execz .LBB0_1026
	s_waitcnt lgkmcnt(0)
	v_add_f32_e32 v98, v98, v99
	global_atomic_add_f32 v[114:115], v98, off offset:64
.LBB0_1026:
	s_or_b64 exec, exec, s[0:1]
	v_add_u32_e32 v106, 32, v144
	v_ashrrev_i32_e32 v107, 31, v106
	s_waitcnt lgkmcnt(0)
	v_lshlrev_b64 v[98:99], 13, v[106:107]
	v_lshl_add_u64 v[98:99], s[60:61], 0, v[98:99]
	v_lshl_add_u64 v[108:109], v[142:143], 2, v[98:99]
	global_load_dwordx4 v[98:101], v[108:109], off nt
	global_load_dwordx4 v[102:105], v[108:109], off offset:16 nt
	global_load_dwordx4 v[170:173], v[108:109], off offset:512 nt
	global_load_dwordx4 v[174:177], v[108:109], off offset:528 nt
	v_lshlrev_b64 v[106:107], 12, v[106:107]
	v_lshl_add_u64 v[106:107], s[62:63], 0, v[106:107]
	v_lshl_add_u64 v[106:107], v[142:143], 1, v[106:107]
	s_waitcnt vmcnt(3)
	v_pk_add_f32 v[100:101], v[96:97], v[100:101]
	v_pk_add_f32 v[98:99], v[94:95], v[98:99]
	s_waitcnt vmcnt(2)
	v_pk_add_f32 v[104:105], v[92:93], v[104:105]
	v_pk_add_f32 v[102:103], v[90:91], v[102:103]
	v_cvt_pk_bf16_f32 v90, v98, v99
	v_cvt_pk_bf16_f32 v91, v100, v101
	v_mul_f32_e32 v99, v99, v99
	v_cvt_pk_bf16_f32 v92, v102, v103
	v_cvt_pk_bf16_f32 v93, v104, v105
	global_store_dwordx4 v[106:107], v[90:93], off
	s_nop 0
	s_nop 0
	s_nop 0
	v_mul_f32_e32 v101, v101, v101
	v_mul_f32_e32 v103, v103, v103
	v_fmac_f32_e32 v99, v98, v98
	v_fmac_f32_e32 v101, v100, v100
	v_mul_f32_e32 v105, v105, v105
	v_fmac_f32_e32 v103, v102, v102
	v_add_f32_e32 v98, v99, v101
	v_fmac_f32_e32 v105, v104, v104
	v_add_f32_e32 v98, v98, v103
	v_add_f32_e32 v98, v105, v98
	s_waitcnt vmcnt(2)
	v_pk_add_f32 v[88:89], v[88:89], v[172:173]
	v_pk_add_f32 v[86:87], v[86:87], v[170:171]
	s_waitcnt vmcnt(1)
	v_pk_add_f32 v[92:93], v[82:83], v[174:175]
	v_mul_f32_e32 v82, v87, v87
	v_mul_f32_e32 v83, v89, v89
	v_pk_add_f32 v[90:91], v[84:85], v[176:177]
	v_mul_f32_e32 v84, v93, v93
	v_fmac_f32_e32 v82, v86, v86
	v_fmac_f32_e32 v83, v88, v88
	v_mul_f32_e32 v85, v91, v91
	v_fmac_f32_e32 v84, v92, v92
	v_add_f32_e32 v82, v82, v83
	v_add_f32_e32 v82, v82, v84
	v_fmac_f32_e32 v85, v90, v90
	v_add_f32_e32 v82, v85, v82
	v_add_f32_e32 v82, v98, v82
	ds_bpermute_b32 v83, v122, v82
	v_cvt_pk_bf16_f32 v84, v86, v87
	v_cvt_pk_bf16_f32 v85, v88, v89
	v_cvt_pk_bf16_f32 v86, v92, v93
	v_cvt_pk_bf16_f32 v87, v90, v91
	s_waitcnt lgkmcnt(0)
	v_add_f32_e32 v82, v82, v83
	ds_bpermute_b32 v83, v116, v82
	global_store_dwordx4 v[106:107], v[84:87], off offset:256
	s_and_saveexec_b64 s[0:1], vcc
	s_cbranch_execz .LBB0_1028
	s_waitcnt lgkmcnt(0)
	v_add_f32_e32 v82, v82, v83
	global_atomic_add_f32 v[114:115], v82, off offset:128
.LBB0_1028:
	s_or_b64 exec, exec, s[0:1]
	v_add_u32_e32 v90, 48, v144
	v_ashrrev_i32_e32 v91, 31, v90
	s_waitcnt lgkmcnt(0)
	v_lshlrev_b64 v[82:83], 13, v[90:91]
	v_lshl_add_u64 v[82:83], s[60:61], 0, v[82:83]
	v_lshl_add_u64 v[92:93], v[142:143], 2, v[82:83]
	global_load_dwordx4 v[82:85], v[92:93], off nt
	global_load_dwordx4 v[86:89], v[92:93], off offset:16 nt
	global_load_dwordx4 v[170:173], v[92:93], off offset:512 nt
	global_load_dwordx4 v[174:177], v[92:93], off offset:528 nt
	v_lshlrev_b64 v[90:91], 12, v[90:91]
	v_lshl_add_u64 v[90:91], s[62:63], 0, v[90:91]
	v_lshl_add_u64 v[90:91], v[142:143], 1, v[90:91]
	s_waitcnt vmcnt(3)
	v_pk_add_f32 v[84:85], v[80:81], v[84:85]
	v_pk_add_f32 v[82:83], v[78:79], v[82:83]
	s_waitcnt vmcnt(2)
	v_pk_add_f32 v[88:89], v[76:77], v[88:89]
	v_pk_add_f32 v[86:87], v[74:75], v[86:87]
	v_cvt_pk_bf16_f32 v74, v82, v83
	v_cvt_pk_bf16_f32 v75, v84, v85
	v_mul_f32_e32 v83, v83, v83
	v_cvt_pk_bf16_f32 v76, v86, v87
	v_cvt_pk_bf16_f32 v77, v88, v89
	global_store_dwordx4 v[90:91], v[74:77], off
	s_nop 0
	s_nop 0
	s_nop 0
	v_mul_f32_e32 v85, v85, v85
	v_mul_f32_e32 v87, v87, v87
	v_fmac_f32_e32 v83, v82, v82
	v_fmac_f32_e32 v85, v84, v84
	v_mul_f32_e32 v89, v89, v89
	v_fmac_f32_e32 v87, v86, v86
	v_add_f32_e32 v82, v83, v85
	v_fmac_f32_e32 v89, v88, v88
	v_add_f32_e32 v82, v82, v87
	v_add_f32_e32 v82, v89, v82
	s_waitcnt vmcnt(2)
	v_pk_add_f32 v[72:73], v[72:73], v[172:173]
	v_pk_add_f32 v[70:71], v[70:71], v[170:171]
	s_waitcnt vmcnt(1)
	v_pk_add_f32 v[76:77], v[66:67], v[174:175]
	v_mul_f32_e32 v66, v71, v71
	v_mul_f32_e32 v67, v73, v73
	v_pk_add_f32 v[74:75], v[68:69], v[176:177]
	v_mul_f32_e32 v68, v77, v77
	v_fmac_f32_e32 v66, v70, v70
	v_fmac_f32_e32 v67, v72, v72
	v_mul_f32_e32 v69, v75, v75
	v_fmac_f32_e32 v68, v76, v76
	v_add_f32_e32 v66, v66, v67
	v_add_f32_e32 v66, v66, v68
	v_fmac_f32_e32 v69, v74, v74
	v_add_f32_e32 v66, v69, v66
	v_add_f32_e32 v66, v82, v66
	ds_bpermute_b32 v67, v122, v66
	v_cvt_pk_bf16_f32 v68, v70, v71
	v_cvt_pk_bf16_f32 v69, v72, v73
	v_cvt_pk_bf16_f32 v70, v76, v77
	v_cvt_pk_bf16_f32 v71, v74, v75
	s_waitcnt lgkmcnt(0)
	v_add_f32_e32 v66, v66, v67
	ds_bpermute_b32 v67, v116, v66
	global_store_dwordx4 v[90:91], v[68:71], off offset:256
	s_and_saveexec_b64 s[0:1], vcc
	s_cbranch_execz .LBB0_1030
	s_waitcnt lgkmcnt(0)
	v_add_f32_e32 v66, v66, v67
	global_atomic_add_f32 v[114:115], v66, off offset:192
.LBB0_1030:
	s_or_b64 exec, exec, s[0:1]
	v_add_u32_e32 v74, 0x80, v144
	v_ashrrev_i32_e32 v75, 31, v74
	s_waitcnt lgkmcnt(0)
	v_lshlrev_b64 v[66:67], 13, v[74:75]
	v_lshl_add_u64 v[66:67], s[60:61], 0, v[66:67]
	v_lshl_add_u64 v[76:77], v[142:143], 2, v[66:67]
	global_load_dwordx4 v[66:69], v[76:77], off nt
	global_load_dwordx4 v[70:73], v[76:77], off offset:16 nt
	global_load_dwordx4 v[170:173], v[76:77], off offset:512 nt
	global_load_dwordx4 v[174:177], v[76:77], off offset:528 nt
	v_lshlrev_b64 v[74:75], 12, v[74:75]
	v_lshl_add_u64 v[74:75], s[62:63], 0, v[74:75]
	v_lshl_add_u64 v[74:75], v[142:143], 1, v[74:75]
	s_waitcnt vmcnt(3)
	v_pk_add_f32 v[68:69], v[64:65], v[68:69]
	v_pk_add_f32 v[66:67], v[62:63], v[66:67]
	s_waitcnt vmcnt(2)
	v_pk_add_f32 v[72:73], v[60:61], v[72:73]
	v_pk_add_f32 v[70:71], v[58:59], v[70:71]
	v_cvt_pk_bf16_f32 v58, v66, v67
	v_cvt_pk_bf16_f32 v59, v68, v69
	v_mul_f32_e32 v67, v67, v67
	v_cvt_pk_bf16_f32 v60, v70, v71
	v_cvt_pk_bf16_f32 v61, v72, v73
	global_store_dwordx4 v[74:75], v[58:61], off
	s_nop 0
	s_nop 0
	s_nop 0
	v_mul_f32_e32 v69, v69, v69
	v_mul_f32_e32 v71, v71, v71
	v_fmac_f32_e32 v67, v66, v66
	v_fmac_f32_e32 v69, v68, v68
	v_mul_f32_e32 v73, v73, v73
	v_fmac_f32_e32 v71, v70, v70
	v_add_f32_e32 v66, v67, v69
	v_fmac_f32_e32 v73, v72, v72
	v_add_f32_e32 v66, v66, v71
	v_add_f32_e32 v66, v73, v66
	s_waitcnt vmcnt(2)
	v_pk_add_f32 v[56:57], v[56:57], v[172:173]
	v_pk_add_f32 v[54:55], v[54:55], v[170:171]
	s_waitcnt vmcnt(1)
	v_pk_add_f32 v[60:61], v[50:51], v[174:175]
	v_mul_f32_e32 v50, v55, v55
	v_mul_f32_e32 v51, v57, v57
	v_pk_add_f32 v[58:59], v[52:53], v[176:177]
	v_mul_f32_e32 v52, v61, v61
	v_fmac_f32_e32 v50, v54, v54
	v_fmac_f32_e32 v51, v56, v56
	v_mul_f32_e32 v53, v59, v59
	v_fmac_f32_e32 v52, v60, v60
	v_add_f32_e32 v50, v50, v51
	v_add_f32_e32 v50, v50, v52
	v_fmac_f32_e32 v53, v58, v58
	v_add_f32_e32 v50, v53, v50
	v_add_f32_e32 v50, v66, v50
	ds_bpermute_b32 v51, v122, v50
	v_cvt_pk_bf16_f32 v52, v54, v55
	v_cvt_pk_bf16_f32 v53, v56, v57
	v_cvt_pk_bf16_f32 v54, v60, v61
	v_cvt_pk_bf16_f32 v55, v58, v59
	s_waitcnt lgkmcnt(0)
	v_add_f32_e32 v50, v50, v51
	ds_bpermute_b32 v51, v116, v50
	global_store_dwordx4 v[74:75], v[52:55], off offset:256
	s_and_saveexec_b64 s[0:1], vcc
	s_cbranch_execz .LBB0_1032
	s_waitcnt lgkmcnt(0)
	v_add_f32_e32 v50, v50, v51
	global_atomic_add_f32 v[114:115], v50, off offset:512
.LBB0_1032:
	s_or_b64 exec, exec, s[0:1]
	v_add_u32_e32 v58, 0x90, v144
	v_ashrrev_i32_e32 v59, 31, v58
	s_waitcnt lgkmcnt(0)
	v_lshlrev_b64 v[50:51], 13, v[58:59]
	v_lshl_add_u64 v[50:51], s[60:61], 0, v[50:51]
	v_lshl_add_u64 v[60:61], v[142:143], 2, v[50:51]
	global_load_dwordx4 v[50:53], v[60:61], off nt
	global_load_dwordx4 v[54:57], v[60:61], off offset:16 nt
	global_load_dwordx4 v[170:173], v[60:61], off offset:512 nt
	global_load_dwordx4 v[174:177], v[60:61], off offset:528 nt
	v_lshlrev_b64 v[58:59], 12, v[58:59]
	v_lshl_add_u64 v[58:59], s[62:63], 0, v[58:59]
	v_lshl_add_u64 v[58:59], v[142:143], 1, v[58:59]
	s_waitcnt vmcnt(3)
	v_pk_add_f32 v[52:53], v[48:49], v[52:53]
	v_pk_add_f32 v[50:51], v[46:47], v[50:51]
	s_waitcnt vmcnt(2)
	v_pk_add_f32 v[56:57], v[44:45], v[56:57]
	v_pk_add_f32 v[54:55], v[42:43], v[54:55]
	v_cvt_pk_bf16_f32 v42, v50, v51
	v_cvt_pk_bf16_f32 v43, v52, v53
	v_mul_f32_e32 v51, v51, v51
	v_cvt_pk_bf16_f32 v44, v54, v55
	v_cvt_pk_bf16_f32 v45, v56, v57
	global_store_dwordx4 v[58:59], v[42:45], off
	s_nop 0
	s_nop 0
	s_nop 0
	v_mul_f32_e32 v53, v53, v53
	v_mul_f32_e32 v55, v55, v55
	v_fmac_f32_e32 v51, v50, v50
	v_fmac_f32_e32 v53, v52, v52
	v_mul_f32_e32 v57, v57, v57
	v_fmac_f32_e32 v55, v54, v54
	v_add_f32_e32 v50, v51, v53
	v_fmac_f32_e32 v57, v56, v56
	v_add_f32_e32 v50, v50, v55
	v_add_f32_e32 v50, v57, v50
	s_waitcnt vmcnt(2)
	v_pk_add_f32 v[40:41], v[40:41], v[172:173]
	v_pk_add_f32 v[38:39], v[38:39], v[170:171]
	s_waitcnt vmcnt(1)
	v_pk_add_f32 v[44:45], v[34:35], v[174:175]
	v_mul_f32_e32 v34, v39, v39
	v_mul_f32_e32 v35, v41, v41
	v_pk_add_f32 v[42:43], v[36:37], v[176:177]
	v_mul_f32_e32 v36, v45, v45
	v_fmac_f32_e32 v34, v38, v38
	v_fmac_f32_e32 v35, v40, v40
	v_mul_f32_e32 v37, v43, v43
	v_fmac_f32_e32 v36, v44, v44
	v_add_f32_e32 v34, v34, v35
	v_add_f32_e32 v34, v34, v36
	v_fmac_f32_e32 v37, v42, v42
	v_add_f32_e32 v34, v37, v34
	v_add_f32_e32 v34, v50, v34
	ds_bpermute_b32 v35, v122, v34
	v_cvt_pk_bf16_f32 v36, v38, v39
	v_cvt_pk_bf16_f32 v37, v40, v41
	v_cvt_pk_bf16_f32 v38, v44, v45
	v_cvt_pk_bf16_f32 v39, v42, v43
	s_waitcnt lgkmcnt(0)
	v_add_f32_e32 v34, v34, v35
	ds_bpermute_b32 v35, v116, v34
	global_store_dwordx4 v[58:59], v[36:39], off offset:256
	s_and_saveexec_b64 s[0:1], vcc
	s_cbranch_execz .LBB0_1034
	s_waitcnt lgkmcnt(0)
	v_add_f32_e32 v34, v34, v35
	global_atomic_add_f32 v[114:115], v34, off offset:576
.LBB0_1034:
	s_or_b64 exec, exec, s[0:1]
	v_add_u32_e32 v42, 0xa0, v144
	v_ashrrev_i32_e32 v43, 31, v42
	s_waitcnt lgkmcnt(0)
	v_lshlrev_b64 v[34:35], 13, v[42:43]
	v_lshl_add_u64 v[34:35], s[60:61], 0, v[34:35]
	v_lshl_add_u64 v[44:45], v[142:143], 2, v[34:35]
	global_load_dwordx4 v[34:37], v[44:45], off nt
	global_load_dwordx4 v[38:41], v[44:45], off offset:16 nt
	global_load_dwordx4 v[170:173], v[44:45], off offset:512 nt
	global_load_dwordx4 v[174:177], v[44:45], off offset:528 nt
	v_lshlrev_b64 v[42:43], 12, v[42:43]
	v_lshl_add_u64 v[42:43], s[62:63], 0, v[42:43]
	v_lshl_add_u64 v[42:43], v[142:143], 1, v[42:43]
	s_waitcnt vmcnt(3)
	v_pk_add_f32 v[36:37], v[32:33], v[36:37]
	v_pk_add_f32 v[34:35], v[30:31], v[34:35]
	s_waitcnt vmcnt(2)
	v_pk_add_f32 v[40:41], v[28:29], v[40:41]
	v_pk_add_f32 v[38:39], v[26:27], v[38:39]
	v_cvt_pk_bf16_f32 v26, v34, v35
	v_cvt_pk_bf16_f32 v27, v36, v37
	v_mul_f32_e32 v35, v35, v35
	v_cvt_pk_bf16_f32 v28, v38, v39
	v_cvt_pk_bf16_f32 v29, v40, v41
	global_store_dwordx4 v[42:43], v[26:29], off
	s_nop 0
	s_nop 0
	s_nop 0
	v_mul_f32_e32 v37, v37, v37
	v_mul_f32_e32 v39, v39, v39
	v_fmac_f32_e32 v35, v34, v34
	v_fmac_f32_e32 v37, v36, v36
	v_mul_f32_e32 v41, v41, v41
	v_fmac_f32_e32 v39, v38, v38
	v_add_f32_e32 v34, v35, v37
	v_fmac_f32_e32 v41, v40, v40
	v_add_f32_e32 v34, v34, v39
	v_add_f32_e32 v34, v41, v34
	s_waitcnt vmcnt(2)
	v_pk_add_f32 v[24:25], v[24:25], v[172:173]
	v_pk_add_f32 v[22:23], v[22:23], v[170:171]
	s_waitcnt vmcnt(1)
	v_pk_add_f32 v[28:29], v[18:19], v[174:175]
	v_mul_f32_e32 v18, v23, v23
	v_mul_f32_e32 v19, v25, v25
	v_pk_add_f32 v[26:27], v[20:21], v[176:177]
	v_mul_f32_e32 v20, v29, v29
	v_fmac_f32_e32 v18, v22, v22
	v_fmac_f32_e32 v19, v24, v24
	v_mul_f32_e32 v21, v27, v27
	v_fmac_f32_e32 v20, v28, v28
	v_add_f32_e32 v18, v18, v19
	v_add_f32_e32 v18, v18, v20
	v_fmac_f32_e32 v21, v26, v26
	v_add_f32_e32 v18, v21, v18
	v_add_f32_e32 v18, v34, v18
	ds_bpermute_b32 v19, v122, v18
	v_cvt_pk_bf16_f32 v20, v22, v23
	v_cvt_pk_bf16_f32 v21, v24, v25
	v_cvt_pk_bf16_f32 v22, v28, v29
	v_cvt_pk_bf16_f32 v23, v26, v27
	s_waitcnt lgkmcnt(0)
	v_add_f32_e32 v18, v18, v19
	ds_bpermute_b32 v19, v116, v18
	global_store_dwordx4 v[42:43], v[20:23], off offset:256
	s_and_saveexec_b64 s[0:1], vcc
	s_cbranch_execz .LBB0_1036
	s_waitcnt lgkmcnt(0)
	v_add_f32_e32 v18, v18, v19
	global_atomic_add_f32 v[114:115], v18, off offset:640
.LBB0_1036:
	s_or_b64 exec, exec, s[0:1]
	v_add_u32_e32 v26, 0xb0, v144
	v_ashrrev_i32_e32 v27, 31, v26
	s_waitcnt lgkmcnt(0)
	v_lshlrev_b64 v[18:19], 13, v[26:27]
	v_lshl_add_u64 v[18:19], s[60:61], 0, v[18:19]
	v_lshl_add_u64 v[28:29], v[142:143], 2, v[18:19]
	global_load_dwordx4 v[18:21], v[28:29], off nt
	global_load_dwordx4 v[22:25], v[28:29], off offset:16 nt
	global_load_dwordx4 v[170:173], v[28:29], off offset:512 nt
	global_load_dwordx4 v[174:177], v[28:29], off offset:528 nt
	v_lshlrev_b64 v[26:27], 12, v[26:27]
	v_lshl_add_u64 v[26:27], s[62:63], 0, v[26:27]
	v_lshl_add_u64 v[26:27], v[142:143], 1, v[26:27]
	s_waitcnt vmcnt(3)
	v_pk_add_f32 v[20:21], v[16:17], v[20:21]
	v_pk_add_f32 v[18:19], v[14:15], v[18:19]
	s_waitcnt vmcnt(2)
	v_pk_add_f32 v[24:25], v[12:13], v[24:25]
	v_pk_add_f32 v[22:23], v[10:11], v[22:23]
	v_cvt_pk_bf16_f32 v10, v18, v19
	v_cvt_pk_bf16_f32 v11, v20, v21
	v_mul_f32_e32 v19, v19, v19
	v_cvt_pk_bf16_f32 v12, v22, v23
	v_cvt_pk_bf16_f32 v13, v24, v25
	global_store_dwordx4 v[26:27], v[10:13], off
	s_nop 0
	s_nop 0
	s_nop 0
	v_mul_f32_e32 v21, v21, v21
	v_mul_f32_e32 v23, v23, v23
	v_fmac_f32_e32 v19, v18, v18
	v_fmac_f32_e32 v21, v20, v20
	v_mul_f32_e32 v25, v25, v25
	v_fmac_f32_e32 v23, v22, v22
	v_add_f32_e32 v18, v19, v21
	v_fmac_f32_e32 v25, v24, v24
	v_add_f32_e32 v18, v18, v23
	v_add_f32_e32 v18, v25, v18
	s_waitcnt vmcnt(2)
	v_pk_add_f32 v[8:9], v[8:9], v[172:173]
	v_pk_add_f32 v[6:7], v[6:7], v[170:171]
	s_waitcnt vmcnt(1)
	v_pk_add_f32 v[12:13], v[2:3], v[174:175]
	v_mul_f32_e32 v2, v7, v7
	v_mul_f32_e32 v3, v9, v9
	v_pk_add_f32 v[10:11], v[4:5], v[176:177]
	v_mul_f32_e32 v4, v13, v13
	v_fmac_f32_e32 v2, v6, v6
	v_fmac_f32_e32 v3, v8, v8
	v_mul_f32_e32 v5, v11, v11
	v_fmac_f32_e32 v4, v12, v12
	v_add_f32_e32 v2, v2, v3
	v_add_f32_e32 v2, v2, v4
	v_fmac_f32_e32 v5, v10, v10
	v_add_f32_e32 v2, v5, v2
	v_add_f32_e32 v2, v18, v2
	ds_bpermute_b32 v3, v122, v2
	v_cvt_pk_bf16_f32 v4, v6, v7
	v_cvt_pk_bf16_f32 v5, v8, v9
	v_cvt_pk_bf16_f32 v6, v12, v13
	v_cvt_pk_bf16_f32 v7, v10, v11
	s_waitcnt lgkmcnt(0)
	v_add_f32_e32 v2, v2, v3
	ds_bpermute_b32 v3, v116, v2
	global_store_dwordx4 v[26:27], v[4:7], off offset:256
	s_and_saveexec_b64 s[0:1], vcc
	s_cbranch_execz .LBB0_1038
	s_waitcnt lgkmcnt(0)
	v_add_f32_e32 v2, v2, v3
	global_atomic_add_f32 v[114:115], v2, off offset:704
